# attention QK: 14-slot K fragment ring with counted lgkmcnt (MFMA/LDS interleave); rnn pass 2 carry compose: all LDS pairs read at once
# speedup vs baseline: 1.0012x; 1.0012x over previous
; #define LAS __attribute__((address_space(3)))
; #define MFMA32(a, b, c) __builtin_amdgcn_mfma_f32_32x32x16_bf16((a), (b), (c), 0, 0, 0)
; DI void attn_unit(LAS unsigned char* lds, bf16_t* P, const float* rope, const float* sinks, int unit, int tid, int wid, int lane) {
;     ...
;         bf16_t* qrow = P + (size_t)(rowblk + r0 + q) * DIN + PC_Q + head * 64;
;         u32x4 qf[4];
; #pragma unroll
;         for (int s = 0; s < 4; ++s) qf[s] = *(const u32x4*)(qrow + 16 * s + 8 * hl);
;         { u32x4 pr; pr.x = __shfl_xor(qf[0].x, 32); pr.y = __shfl_xor(qf[0].y, 32); pr.z = __shfl_xor(qf[0].z, 32); pr.w = __shfl_xor(qf[0].w, 32);
;           rope8(qf[0], pr, rope + (n * 128 + r0 + q) * 16, hl == 1); }
;         f32x16 S[5];
; #pragma unroll
;         for (int kt = 0; kt < 5; ++kt) {
; #pragma unroll
;             for (int i = 0; i < 16; ++i) S[kt][i] = 0.f;
; #pragma unroll
;             for (int s = 0; s < 4; ++s) { const bf16x8 kf = *(const LAS bf16x8*)(Ks + (r0 + 32 * kt + q) * KS_LD + 16 * s + 8 * hl);
;                 S[kt] = MFMA32(kf, __builtin_bit_cast(bf16x8, qf[s]), S[kt]); }
;         }
.LBB0_303:
	v_lshl_add_u64 v[0:1], v[108:109], 0, s[82:83]
	v_add_co_u32_e32 v112, vcc, 0x10400000, v0
	s_nop 1
	v_addc_co_u32_e32 v113, vcc, 0, v1, vcc
	flat_load_dwordx4 v[0:3], v[112:113]
	flat_load_dwordx4 v[4:7], v[106:107] offset:32
	flat_load_dwordx4 v[8:11], v[106:107] offset:48
	flat_load_dwordx4 v[12:15], v[106:107]
	flat_load_dwordx4 v[16:19], v[106:107] offset:16
	flat_load_dwordx4 v[82:85], v[112:113] offset:32
	flat_load_dwordx4 v[86:89], v[112:113] offset:64
	ds_read_b128 v[176:179], v128
	ds_read_b128 v[180:183], v128 offset:32
	ds_read_b128 v[184:187], v128 offset:4608
	ds_read_b128 v[188:191], v128 offset:4640
	ds_read_b128 v[192:195], v128 offset:9216
	ds_read_b128 v[196:199], v128 offset:9248
	ds_read_b128 v[200:203], v128 offset:13824
	ds_read_b128 v[204:207], v128 offset:13856
	ds_read_b128 v[208:211], v128 offset:18432
	ds_read_b128 v[212:215], v128 offset:18464
	ds_read_b128 v[216:219], v128 offset:64
	ds_read_b128 v[220:223], v128 offset:4672
	ds_read_b128 v[224:227], v128 offset:9280
	ds_read_b128 v[228:231], v128 offset:13888
	flat_load_dwordx4 v[136:139], v[112:113] offset:96
	s_andn2_b64 vcc, exec, s[94:95]
	s_waitcnt vmcnt(0) lgkmcnt(0)
	ds_bpermute_b32 v28, v120, v0
	ds_bpermute_b32 v29, v120, v1
	ds_bpermute_b32 v30, v120, v2
	ds_bpermute_b32 v31, v120, v3
	v_lshlrev_b32_e32 v24, 16, v0
	s_waitcnt lgkmcnt(3)
	v_lshlrev_b32_e32 v32, 16, v28
	v_and_b32_e32 v28, 0xffff0000, v28
	s_waitcnt lgkmcnt(2)
	v_lshlrev_b32_e32 v33, 16, v29
	v_and_b32_e32 v34, 0xffff0000, v29
	s_waitcnt lgkmcnt(1)
	v_lshlrev_b32_e32 v35, 16, v30
	v_and_b32_e32 v36, 0xffff0000, v30
	s_waitcnt lgkmcnt(0)
	v_lshlrev_b32_e32 v37, 16, v31
	v_and_b32_e32 v38, 0xffff0000, v31
	v_cndmask_b32_e64 v29, -v28, v28, s[48:49]
	v_cndmask_b32_e64 v28, -v32, v32, s[48:49]
	v_cndmask_b32_e64 v31, -v34, v34, s[48:49]
	v_cndmask_b32_e64 v30, -v33, v33, s[48:49]
	v_cndmask_b32_e64 v33, -v36, v36, s[48:49]
	v_cndmask_b32_e64 v32, -v35, v35, s[48:49]
	v_cndmask_b32_e64 v35, -v38, v38, s[48:49]
	v_cndmask_b32_e64 v34, -v37, v37, s[48:49]
	v_and_b32_e32 v25, 0xffff0000, v0
	v_lshlrev_b32_e32 v0, 16, v1
	v_and_b32_e32 v1, 0xffff0000, v1
	v_lshlrev_b32_e32 v26, 16, v2
	v_and_b32_e32 v27, 0xffff0000, v2
	v_lshlrev_b32_e32 v2, 16, v3
	v_and_b32_e32 v3, 0xffff0000, v3
	v_pk_mul_f32 v[4:5], v[28:29], v[4:5]
	v_pk_mul_f32 v[6:7], v[30:31], v[6:7]
	v_pk_mul_f32 v[8:9], v[32:33], v[8:9]
	v_pk_mul_f32 v[10:11], v[34:35], v[10:11]
	v_pk_fma_f32 v[4:5], v[12:13], v[24:25], v[4:5]
	v_pk_fma_f32 v[0:1], v[14:15], v[0:1], v[6:7]
	v_pk_fma_f32 v[6:7], v[16:17], v[26:27], v[8:9]
	v_pk_fma_f32 v[2:3], v[18:19], v[2:3], v[10:11]
	v_cvt_pk_bf16_f32 v48, v4, v5
	v_cvt_pk_bf16_f32 v49, v0, v1
	v_cvt_pk_bf16_f32 v50, v6, v7
	v_cvt_pk_bf16_f32 v51, v2, v3
	s_nop 1
	v_mfma_f32_32x32x16_bf16 v[64:79], v[176:179], v[48:51], 0
	ds_read_b128 v[176:179], v128 offset:18496
	v_mfma_f32_32x32x16_bf16 v[64:79], v[180:183], v[82:85], v[64:79]
	ds_read_b128 v[180:183], v128 offset:96
	v_mfma_f32_32x32x16_bf16 v[32:47], v[184:187], v[48:51], 0
	ds_read_b128 v[184:187], v128 offset:4704
	v_mfma_f32_32x32x16_bf16 v[32:47], v[188:191], v[82:85], v[32:47]
	ds_read_b128 v[188:191], v128 offset:9312
	v_mfma_f32_32x32x16_bf16 v[16:31], v[192:195], v[48:51], 0
	ds_read_b128 v[192:195], v128 offset:13920
	v_mfma_f32_32x32x16_bf16 v[16:31], v[196:199], v[82:85], v[16:31]
	ds_read_b128 v[196:199], v128 offset:18528
	v_mfma_f32_32x32x16_bf16 v[0:15], v[200:203], v[48:51], 0
	v_mfma_f32_32x32x16_bf16 v[0:15], v[204:207], v[82:85], v[0:15]
	v_mfma_f32_32x32x16_bf16 v[48:63], v[208:211], v[48:51], 0
	v_mfma_f32_32x32x16_bf16 v[48:63], v[212:215], v[82:85], v[48:63]
	v_mfma_f32_32x32x16_bf16 v[64:79], v[216:219], v[86:89], v[64:79]
	v_mfma_f32_32x32x16_bf16 v[32:47], v[220:223], v[86:89], v[32:47]
	v_mfma_f32_32x32x16_bf16 v[16:31], v[224:227], v[86:89], v[16:31]
	v_mfma_f32_32x32x16_bf16 v[0:15], v[228:231], v[86:89], v[0:15]
	s_waitcnt lgkmcnt(5)
	v_mfma_f32_32x32x16_bf16 v[48:63], v[176:179], v[86:89], v[48:63]
	s_waitcnt lgkmcnt(4)
	v_mfma_f32_32x32x16_bf16 v[64:79], v[180:183], v[136:139], v[64:79]
	s_waitcnt lgkmcnt(3)
	v_mfma_f32_32x32x16_bf16 v[32:47], v[184:187], v[136:139], v[32:47]
	s_waitcnt lgkmcnt(2)
	v_mfma_f32_32x32x16_bf16 v[16:31], v[188:191], v[136:139], v[16:31]
	s_waitcnt lgkmcnt(1)
	v_mfma_f32_32x32x16_bf16 v[0:15], v[192:195], v[136:139], v[0:15]
	s_waitcnt lgkmcnt(0)
	v_mfma_f32_32x32x16_bf16 v[48:63], v[196:199], v[136:139], v[48:63]
	s_nop 3
	s_cbranch_vccnz .LBB0_305
	v_cndmask_b32_e64 v82, v170, v64, s[50:51]
	v_cndmask_b32_e64 v113, v65, v170, s[52:53]
	v_cndmask_b32_e64 v112, v170, v66, s[54:55]
	v_cndmask_b32_e64 v89, v170, v67, s[56:57]
	v_cndmask_b32_e64 v88, v170, v68, s[58:59]
	v_cndmask_b32_e64 v87, v170, v69, s[60:61]
	v_cndmask_b32_e64 v86, v170, v70, s[62:63]
	v_cndmask_b32_e64 v85, v170, v71, s[64:65]
	v_cndmask_b32_e64 v84, v170, v72, s[66:67]
	v_cndmask_b32_e64 v83, v170, v73, s[68:69]
	v_cndmask_b32_e64 v74, v170, v74, s[70:71]
	v_cndmask_b32_e64 v73, v170, v75, s[72:73]
	v_cndmask_b32_e64 v72, v170, v76, s[74:75]
	v_cndmask_b32_e64 v71, v170, v77, s[76:77]
	v_cndmask_b32_e64 v70, v170, v78, s[78:79]
	v_cndmask_b32_e64 v69, v170, v79, s[80:81]
	s_add_i32 s96, s23, 1
	s_cbranch_execnz .LBB0_302
	s_branch .LBB0_306

; #define LAS __attribute__((address_space(3)))
; DI void rnn_phase(LAS unsigned char* lds, bf16_t* P, const bf16_t* WaT, const bf16_t* WiT, const float* convw, const float* convb, const float* ba, const float* bi, const float* lam,
;                   f32x2* sums, unsigned* au, bool fin, int bx, int G, int tid, int wid, int lane) {
;     ...
;             for (int j = 0; j < 16; ++j) { const h2_t v = __builtin_bit_cast(h2_t, w[j]); av[j] = 1.0f - (float)v.x; uv[j] = (float)v.y; H = av[j] * H + uv[j]; A *= av[j]; }
;             LAS float* SGp = SG + (par ? 2048 : 0);
;             SGp[seg * 64 + ch] = A; SGp[512 + seg * 64 + ch] = H; SGp[1024 + wid * 64 + lane] = Ap; SGp[1536 + wid * 64 + lane] = Hp;
;             __syncthreads();
;             float h = 0.f;
; #pragma unroll
;             for (int q8 = 0; q8 < 8; ++q8) h = SGp[1024 + q8 * 64 + ch] * h + SGp[1536 + q8 * 64 + ch];
;             for (int s2 = 0; s2 < seg; ++s2) h = SGp[s2 * 64 + ch] * h + SGp[512 + s2 * 64 + ch];
.Lr2_pfset:
	s_nop 0
	v_writelane_b32 v234, s25, 6
	v_cvt_f32_f16_e32 v6, v60
	v_cvt_f32_f16_e32 v4, v53
	v_cvt_f32_f16_e32 v5, v56
	s_cmp_eq_u32 s20, 0
	v_sub_f32_e32 v80, 1.0, v6
	v_cvt_f32_f16_e32 v6, v62
	v_sub_f32_e32 v83, 1.0, v4
	v_fma_mix_f32 v4, v83, 0, v53 op_sel:[0,0,1] op_sel_hi:[0,0,1]
	v_sub_f32_e32 v82, 1.0, v5
	v_sub_f32_e32 v79, 1.0, v6
	v_cvt_f32_f16_e32 v6, v63
	v_fma_mix_f32 v4, v4, v82, v56 op_sel:[0,0,1] op_sel_hi:[0,0,1]
	v_mul_f32_e32 v5, v83, v82
	v_fma_mix_f32 v4, v4, v80, v60 op_sel:[0,0,1] op_sel_hi:[0,0,1]
	v_sub_f32_e32 v76, 1.0, v6
	v_cvt_f32_f16_e32 v6, v65
	v_mul_f32_e32 v5, v5, v80
	v_fma_mix_f32 v4, v4, v79, v62 op_sel:[0,0,1] op_sel_hi:[0,0,1]
	v_mul_f32_e32 v5, v5, v79
	v_sub_f32_e32 v72, 1.0, v6
	v_cvt_f32_f16_e32 v6, v67
	v_fma_mix_f32 v4, v4, v76, v63 op_sel:[0,0,1] op_sel_hi:[0,0,1]
	v_mul_f32_e32 v5, v5, v76
	v_fma_mix_f32 v4, v4, v72, v65 op_sel:[0,0,1] op_sel_hi:[0,0,1]
	v_sub_f32_e32 v66, 1.0, v6
	v_cvt_f32_f16_e32 v6, v68
	v_mul_f32_e32 v5, v5, v72
	v_fma_mix_f32 v4, v4, v66, v67 op_sel:[0,0,1] op_sel_hi:[0,0,1]
	v_mul_f32_e32 v5, v5, v66
	v_sub_f32_e32 v61, 1.0, v6
	v_cvt_f32_f16_e32 v6, v69
	v_fma_mix_f32 v4, v4, v61, v68 op_sel:[0,0,1] op_sel_hi:[0,0,1]
	v_mul_f32_e32 v5, v5, v61
	s_cselect_b32 s21, 0, 0x2000
	v_sub_f32_e32 v59, 1.0, v6
	v_cvt_f32_f16_e32 v6, v70
	v_fma_mix_f32 v4, v4, v59, v69 op_sel:[0,0,1] op_sel_hi:[0,0,1]
	v_mul_f32_e32 v5, v5, v59
	s_add_i32 s21, s21, 0
	v_sub_f32_e32 v57, 1.0, v6
	v_cvt_f32_f16_e32 v6, v71
	v_fma_mix_f32 v4, v4, v57, v70 op_sel:[0,0,1] op_sel_hi:[0,0,1]
	v_mul_f32_e32 v5, v5, v57
	s_add_i32 s21, s21, 0x19000
	v_sub_f32_e32 v54, 1.0, v6
	v_cvt_f32_f16_e32 v6, v73
	v_fma_mix_f32 v4, v4, v54, v71 op_sel:[0,0,1] op_sel_hi:[0,0,1]
	v_mul_f32_e32 v5, v5, v54
	s_add_i32 s22, s21, s19
	v_sub_f32_e32 v52, 1.0, v6
	v_cvt_f32_f16_e32 v6, v74
	v_fma_mix_f32 v4, v4, v52, v73 op_sel:[0,0,1] op_sel_hi:[0,0,1]
	v_mul_f32_e32 v5, v5, v52
	s_andn2_b64 vcc, exec, s[30:31]
	v_sub_f32_e32 v50, 1.0, v6
	v_cvt_f32_f16_e32 v6, v75
	v_fma_mix_f32 v4, v4, v50, v74 op_sel:[0,0,1] op_sel_hi:[0,0,1]
	v_mul_f32_e32 v5, v5, v50
	v_sub_f32_e32 v48, 1.0, v6
	v_cvt_f32_f16_e32 v6, v77
	v_fma_mix_f32 v4, v4, v48, v75 op_sel:[0,0,1] op_sel_hi:[0,0,1]
	v_mul_f32_e32 v5, v5, v48
	v_sub_f32_e32 v46, 1.0, v6
	v_cvt_f32_f16_e32 v6, v78
	v_fma_mix_f32 v4, v4, v46, v77 op_sel:[0,0,1] op_sel_hi:[0,0,1]
	v_mul_f32_e32 v5, v5, v46
	v_sub_f32_e32 v45, 1.0, v6
	v_lshlrev_b32_e32 v6, 2, v64
	v_fma_mix_f32 v4, v4, v45, v78 op_sel:[0,0,1] op_sel_hi:[0,0,1]
	v_mul_f32_e32 v5, v5, v45
	v_add_u32_e32 v7, s22, v6
	ds_write2st64_b32 v7, v5, v4 offset1:8
	ds_write2st64_b32 v7, v2, v3 offset0:16 offset1:24
	v_add_u32_e32 v2, s21, v6
	s_waitcnt lgkmcnt(0)
	s_barrier
	ds_read2st64_b32 v[92:93], v2 offset0:16 offset1:17
	ds_read2st64_b32 v[100:101], v2 offset0:24 offset1:25
	ds_read2st64_b32 v[94:95], v2 offset0:18 offset1:19
	ds_read2st64_b32 v[102:103], v2 offset0:26 offset1:27
	ds_read2st64_b32 v[96:97], v2 offset0:20 offset1:21
	ds_read2st64_b32 v[104:105], v2 offset0:28 offset1:29
	ds_read2st64_b32 v[98:99], v2 offset0:22 offset1:23
	ds_read2st64_b32 v[106:107], v2 offset0:30 offset1:31
	ds_read2st64_b32 v[108:109], v2 offset1:1
	ds_read2st64_b32 v[116:117], v2 offset0:8 offset1:9
	ds_read2st64_b32 v[110:111], v2 offset0:2 offset1:3
	ds_read2st64_b32 v[118:119], v2 offset0:10 offset1:11
	ds_read2st64_b32 v[112:113], v2 offset0:4 offset1:5
	ds_read2st64_b32 v[120:121], v2 offset0:12 offset1:13
	ds_read2st64_b32 v[114:115], v2 offset0:6 offset1:7
	ds_read2st64_b32 v[122:123], v2 offset0:14 offset1:15
	s_waitcnt lgkmcnt(0)
	v_fma_f32 v31, 0, v92, v100
	v_fma_f32 v31, v31, v93, v101
	v_fma_f32 v31, v31, v94, v102
	v_fma_f32 v31, v31, v95, v103
	v_fma_f32 v31, v31, v96, v104
	v_fma_f32 v31, v31, v97, v105
	v_fma_f32 v31, v31, v98, v106
	v_fma_f32 v31, v31, v99, v107
	s_cmp_le_u32 s7, 0
	s_cbranch_scc1 .LBB0_368
	v_fma_f32 v31, v31, v108, v116
	s_cmp_le_u32 s7, 1
	s_cbranch_scc1 .LBB0_368
	v_fma_f32 v31, v31, v109, v117
	s_cmp_le_u32 s7, 2
	s_cbranch_scc1 .LBB0_368
	v_fma_f32 v31, v31, v110, v118
	s_cmp_le_u32 s7, 3
	s_cbranch_scc1 .LBB0_368
	v_fma_f32 v31, v31, v111, v119
	s_cmp_le_u32 s7, 4
	s_cbranch_scc1 .LBB0_368
	v_fma_f32 v31, v31, v112, v120
	s_cmp_le_u32 s7, 5
	s_cbranch_scc1 .LBB0_368
	v_fma_f32 v31, v31, v113, v121
	s_cmp_le_u32 s7, 6
	s_cbranch_scc1 .LBB0_368
	v_fma_f32 v31, v31, v114, v122
	s_branch .LBB0_368
